# late weight transposes done at the end of the hyena phase by the 128 blocks without a chunk-state GEMM unit (idle there) instead of in the carry-scan phase
# speedup vs baseline: 1.0255x; 1.0063x over previous
.LBB0_492:
	s_waitcnt vmcnt(0) lgkmcnt(0)
	s_barrier
	s_cmpk_lt_i32 s6, 0x80
	s_cbranch_scc1 .Llt_p3_skip
	s_mov_b32 s101, 1
	s_branch .Llt_block
.Llt_p3_return:
	s_mov_b32 s101, 0
.Llt_p3_skip:
	s_waitcnt vmcnt(0)
	s_barrier
	s_mov_b64 s[0:1], exec
	v_readlane_b32 s2, v248, 3
	v_readlane_b32 s3, v248, 4
	s_and_b64 s[2:3], s[0:1], s[2:3]
	s_mov_b64 exec, s[2:3]
	s_cbranch_execz .LBB0_544
	v_readlane_b32 s98, v248, 1
	v_readlane_b32 s99, v248, 2
	v_mov_b32_e32 v0, 0x20ff0
	ds_read2_b32 v[2:3], v0 offset1:1
	v_mov_b32_e32 v1, 1
	v_mov_b32_e32 v4, s97
	v_lshlrev_b32_e32 v4, 8, v4
	s_add_u32 s98, s98, 0x1000
	s_addc_u32 s99, s99, 0
	s_nop 2
	global_atomic_add v5, v4, v1, s[98:99] offset:1024 sc0
	s_waitcnt vmcnt(0) lgkmcnt(0)
	v_mul_u32_u24_e32 v2, 4, v2
	v_mul_u32_u24_e32 v3, 4, v3
	v_add_u32_e32 v5, 1, v5
	v_cmp_ne_u32_e32 vcc, v5, v2
	v_mov_b32_e32 v6, 0x2400
	s_cbranch_vccnz .Lxb3_poll
	buffer_wbl2 sc1
	s_waitcnt vmcnt(0)
	global_atomic_add v6, v1, s[98:99]

.LBB0_556:
	s_mov_b32 s101, 2
.Llt_block:
	v_mov_b32_e32 v0, v193
	s_mov_b32 s1, 0
	v_readfirstlane_b32 s0, v0
	s_ashr_i32 s0, s0, 6
	s_mul_i32 s2, s0, 0x2400
	s_add_i32 s4, s2, 0
	s_cmp_lt_i32 s0, 4
	s_cselect_b64 s[8:9], -1, 0
	s_lshl_b32 s5, s6, 2
	s_add_i32 s3, s3, s5
	s_add_i32 s3, s3, s0
	s_lshl_b32 s0, s0, 1
	s_add_i32 s7, s96, s0
	s_add_i32 s7, s7, -8
	s_add_u32 s14, s90, 0x17e0000
	s_addc_u32 s15, s91, 0
	s_add_u32 s16, s90, 0xce0000
	s_addc_u32 s17, s91, 0
	s_add_u32 s12, s90, 0xae0000
	s_addc_u32 s13, s91, 0
	s_add_u32 s38, s90, 0x9e0000
	s_waitcnt lgkmcnt(0)
	v_bfe_u32 v28, v0, 5, 1
	v_lshlrev_b32_e32 v2, 2, v0
	s_waitcnt vmcnt(0)
	v_bfe_u32 v92, v0, 3, 3
	v_lshlrev_b32_e32 v0, 3, v0
	s_addc_u32 s39, s91, 0
	v_mul_u32_u24_e32 v1, 0x84, v28
	v_and_b32_e32 v24, 0x7c, v2
	v_and_b32_e32 v0, 56, v0
	s_add_u32 s40, s90, 0x8e0000
	v_add3_u32 v29, s4, v1, v24
	v_mul_u32_u24_e32 v4, 0x84, v0
	v_mov_b32_e32 v1, 0
	v_lshlrev_b32_e32 v5, 2, v92
	s_addc_u32 s41, s91, 0
	v_add3_u32 v93, s4, v4, v5
	s_add_u32 s4, s90, 0x860000
	v_mov_b32_e32 v25, v1
	v_lshlrev_b32_e32 v0, 1, v0
	s_addc_u32 s5, s91, 0
	v_lshl_add_u64 v[18:19], s[80:81], 0, v[24:25]
	v_readlane_b32 s80, v248, 3
	s_mul_i32 s2, s92, 12
	v_or_b32_e32 v30, 2, v28
	v_add_u32_e32 v31, 0x108, v29
	v_or_b32_e32 v32, 4, v28
	v_add_u32_e32 v33, 0x210, v29
	v_or_b32_e32 v34, 6, v28
	v_add_u32_e32 v35, 0x318, v29
	v_or_b32_e32 v36, 8, v28
	v_add_u32_e32 v37, 0x420, v29
	v_or_b32_e32 v38, 10, v28
	v_add_u32_e32 v39, 0x528, v29
	v_or_b32_e32 v40, 12, v28
	v_add_u32_e32 v41, 0x630, v29
	v_or_b32_e32 v42, 14, v28
	v_add_u32_e32 v43, 0x738, v29
	v_or_b32_e32 v44, 16, v28
	v_add_u32_e32 v45, 0x840, v29
	v_or_b32_e32 v46, 18, v28
	v_add_u32_e32 v47, 0x948, v29
	v_or_b32_e32 v48, 20, v28
	v_add_u32_e32 v49, 0xa50, v29
	v_or_b32_e32 v50, 22, v28
	v_add_u32_e32 v51, 0xb58, v29
	v_or_b32_e32 v52, 24, v28
	v_add_u32_e32 v53, 0xc60, v29
	v_or_b32_e32 v54, 26, v28
	v_add_u32_e32 v55, 0xd68, v29
	v_or_b32_e32 v56, 28, v28
	v_add_u32_e32 v57, 0xe70, v29
	v_or_b32_e32 v58, 30, v28
	v_add_u32_e32 v59, 0xf78, v29
	v_or_b32_e32 v60, 32, v28
	v_add_u32_e32 v61, 0x1080, v29
	v_or_b32_e32 v62, 34, v28
	v_add_u32_e32 v63, 0x1188, v29
	v_or_b32_e32 v64, 36, v28
	v_add_u32_e32 v65, 0x1290, v29
	v_or_b32_e32 v66, 38, v28
	v_add_u32_e32 v67, 0x1398, v29
	v_or_b32_e32 v68, 40, v28
	v_add_u32_e32 v69, 0x14a0, v29
	v_or_b32_e32 v70, 42, v28
	v_add_u32_e32 v71, 0x15a8, v29
	v_or_b32_e32 v72, 44, v28
	v_add_u32_e32 v73, 0x16b0, v29
	v_or_b32_e32 v74, 46, v28
	v_add_u32_e32 v75, 0x17b8, v29
	v_or_b32_e32 v76, 48, v28
	v_add_u32_e32 v77, 0x18c0, v29
	v_or_b32_e32 v78, 50, v28
	v_add_u32_e32 v79, 0x19c8, v29
	v_or_b32_e32 v80, 52, v28
	v_add_u32_e32 v81, 0x1ad0, v29
	v_or_b32_e32 v82, 54, v28
	v_add_u32_e32 v83, 0x1bd8, v29
	v_or_b32_e32 v84, 56, v28
	v_add_u32_e32 v85, 0x1ce0, v29
	v_or_b32_e32 v86, 58, v28
	v_add_u32_e32 v87, 0x1de8, v29
	v_or_b32_e32 v88, 60, v28
	v_add_u32_e32 v89, 0x1ef0, v29
	v_or_b32_e32 v90, 62, v28
	v_add_u32_e32 v91, 0x1ff8, v29
	v_lshl_add_u64 v[2:3], s[14:15], 0, v[0:1]
	v_or_b32_e32 v94, 8, v92
	v_or_b32_e32 v95, 16, v92
	v_or_b32_e32 v96, 24, v92
	v_lshl_add_u64 v[4:5], s[16:17], 0, v[0:1]
	v_lshl_add_u64 v[6:7], s[12:13], 0, v[0:1]
	v_lshl_add_u64 v[8:9], s[38:39], 0, v[0:1]
	v_lshl_add_u64 v[10:11], s[40:41], 0, v[0:1]
	v_lshl_add_u64 v[12:13], s[4:5], 0, v[0:1]
	v_lshl_add_u64 v[14:15], s[84:85], 0, v[24:25]
	v_lshl_add_u64 v[16:17], s[82:83], 0, v[24:25]
	v_lshl_add_u64 v[20:21], s[78:79], 0, v[24:25]
	v_lshl_add_u64 v[22:23], s[76:77], 0, v[24:25]
	v_lshl_add_u64 v[24:25], s[30:31], 0, v[24:25]
	v_mov_b32_e32 v97, 0x100
	s_mov_b32 s33, 0
	v_readlane_b32 s81, v248, 4
	s_cmp_eq_u32 s101, 2
	s_cbranch_scc1 .LBB0_589
	v_readfirstlane_b32 s34, v193
	s_nop 3
	s_lshr_b32 s34, s34, 6
	s_sub_i32 s0, s6, 0x80
	s_lshl_b32 s0, s0, 3
	s_add_i32 s34, s34, s0
	s_movk_i32 s2, 0x400
	s_mov_b32 s33, 2
	s_branch .Llt_inner

.Llt_inner:
	s_lshl_b32 s35, s34, 5
	s_lshl_b32 s42, s2, 5
	s_lshl_b32 s43, s34, 1
	s_lshl_b32 s44, s2, 1
	s_branch .LBB0_569

.LBB0_589:
	s_cmp_eq_u32 s101, 1
	s_cbranch_scc1 .Llt_p3_return
	s_waitcnt vmcnt(0)
	s_barrier
	s_and_saveexec_b64 s[0:1], s[80:81]
	s_cbranch_execz .LBB0_641
	v_readlane_b32 s98, v248, 1
	v_readlane_b32 s99, v248, 2
	v_mov_b32_e32 v0, 0x20ff0
	ds_read2_b32 v[2:3], v0 offset1:1
	v_mov_b32_e32 v1, 1
	v_mov_b32_e32 v4, s97
	v_lshlrev_b32_e32 v4, 8, v4
	s_add_u32 s98, s98, 0x1000
	s_addc_u32 s99, s99, 0
	s_nop 2
	global_atomic_add v5, v4, v1, s[98:99] offset:1024 sc0
	s_waitcnt vmcnt(0) lgkmcnt(0)
	v_mul_u32_u24_e32 v2, 5, v2
	v_mul_u32_u24_e32 v3, 5, v3
	v_add_u32_e32 v5, 1, v5
	v_cmp_ne_u32_e32 vcc, v5, v2
	v_mov_b32_e32 v6, 0x2400
	s_cbranch_vccnz .Lxb4_poll
	buffer_wbl2 sc1
	s_waitcnt vmcnt(0)
	global_atomic_add v6, v1, s[98:99]
